# attention: V tile global loads remapped so each wave reads 4 adjacent 16B chunks per key row (64B/row) instead of chunks 128B apart
# baseline (speedup 1.0000x reference)
.LBB0_348:
	s_or_b64 exec, exec, s[14:15]
	v_cndmask_b32_e64 v8, 0, 1, s[8:9]
	v_cmp_ne_u32_e64 s[38:39], 1, v8
	v_ashrrev_i32_e32 v60, 3, v50
	v_add_u32_e32 v59, 0x200, v50
	v_add_u32_e32 v8, 0x400, v50
	v_add_u32_e32 v58, 0x600, v50
	s_mov_b64 s[14:15], -1
	s_andn2_b64 vcc, exec, s[8:9]
	v_ashrrev_i32_e32 v102, 5, v50
	v_lshlrev_b32_e32 v61, 4, v50
	v_and_b32_e32 v104, -8, v60
	v_ashrrev_i32_e32 v106, 5, v59
	v_ashrrev_i32_e32 v57, 3, v59
	v_ashrrev_i32_e32 v108, 5, v8
	v_ashrrev_i32_e32 v56, 3, v8
	v_ashrrev_i32_e32 v110, 5, v58
	v_ashrrev_i32_e32 v55, 3, v58
	v_and_b32_e32 v104, -2, v102
	v_lshlrev_b32_e32 v104, 4, v104
	v_add_u32_e32 v57, 8, v104
	v_add_u32_e32 v56, 16, v104
	v_add_u32_e32 v55, 24, v104
	s_cbranch_vccz .LBB0_390
	s_andn2_b64 vcc, exec, s[14:15]
	v_ashrrev_i32_e32 v103, 31, v102
	s_cbranch_vccz .LBB0_391

; #define LAS __attribute__((address_space(3)))
; __device__ __forceinline__ void attn_item(const Params& P, int l, LAS unsigned char* lds, int item, const int wv) {
;     ...
;             { const int idx = tid + 512 * i, key = idx >> 5, hc = idx & 31, hh = hc >> 4, ch = hc & 15;
;               *(LAS u32x4*)(Kl + (hh * 64 + key) * 136 + 8 * ch) = kreg[i]; }
;             { const int idx = tid + 512 * i, key = idx & 63, hc = idx >> 6, hh = hc >> 4, ch = hc & 15; const u32x4 vv = vreg[i];
;               LAS bf16_t* d = Vt + (hh * 128 + 8 * ch) * 72 + key;
;               d[0 * 72] = (bf16_t)(vv.x & 0xffffu); d[1 * 72] = (bf16_t)(vv.x >> 16); d[2 * 72] = (bf16_t)(vv.y & 0xffffu); d[3 * 72] = (bf16_t)(vv.y >> 16);
;               d[4 * 72] = (bf16_t)(vv.z & 0xffffu); d[5 * 72] = (bf16_t)(vv.z >> 16); d[6 * 72] = (bf16_t)(vv.w & 0xffffu); d[7 * 72] = (bf16_t)(vv.w >> 16); }
.LBB0_351:
	v_lshlrev_b32_e32 v8, 2, v50
	v_and_b32_e32 v8, 64, v8
	v_lshlrev_b32_e32 v62, 3, v50
	v_and_b32_e32 v114, 63, v50
	v_lshl_add_u32 v69, v54, 4, 16
	v_lshlrev_b32_e32 v101, 2, v54
	v_mov_b32_e32 v54, s7
	v_lshrrev_b32_e32 v50, 3, v50
	v_mad_i32_i24 v113, v53, s42, v54
	v_add_u32_e32 v54, v8, v102
	s_movk_i32 s21, 0x110
	v_and_b32_e32 v50, 0x78, v50
	s_mov_b32 s14, 0xfffff80
	v_mul_lo_u32 v71, v54, s21
	v_and_or_b32 v54, v60, s14, v50
	s_movk_i32 s19, 0x90
	v_mul_lo_u32 v60, v54, s19
	v_add_u32_e32 v54, v106, v8
	v_mul_lo_u32 v72, v54, s21
	v_lshrrev_b32_e32 v54, 3, v59
	v_and_b32_e32 v54, 0x78, v54
	v_and_or_b32 v54, v57, s14, v54
	v_mul_lo_u32 v59, v54, s19
	v_add_u32_e32 v54, v108, v8
	v_add_u32_e32 v8, v110, v8
	v_mul_lo_u32 v74, v8, s21
	v_lshrrev_b32_e32 v8, 3, v58
	s_lshl_b32 s8, s29, 4
	v_and_b32_e32 v8, 0x78, v8
	s_add_i32 s18, s8, 0x2000
	v_and_or_b32 v8, v55, s14, v8
	v_and_b32_e32 v67, 0xf8, v62
	v_mov_b64_e32 v[62:63], s[30:31]
	v_mul_lo_u32 v58, v8, s19
	v_add_u32_e32 v8, s18, v102
	s_lshl_b32 s82, s28, 8
	v_mul_lo_u32 v73, v54, s21
	v_and_or_b32 v50, v56, s14, v50
	v_and_b32_e32 v120, -8, v55
	v_mad_i64_i32 v[54:55], s[14:15], v8, s13, v[62:63]
	v_lshl_add_u64 v[54:55], v[54:55], 0, s[82:83]
	v_lshlrev_b32_e32 v8, 1, v67
	v_lshl_add_u64 v[122:123], v[54:55], 0, v[8:9]
	v_add_u32_e32 v54, s18, v106
	v_mad_i64_i32 v[54:55], s[14:15], v54, s13, v[62:63]
	v_lshl_add_u64 v[54:55], v[54:55], 0, s[82:83]
	v_lshl_add_u64 v[126:127], v[54:55], 0, v[8:9]
	v_add_u32_e32 v54, s18, v108
	v_or_b32_e32 v64, s18, v114
	v_mad_i64_i32 v[54:55], s[14:15], v54, s13, v[62:63]
	v_mad_u64_u32 v[64:65], s[8:9], v64, s13, v[62:63]
	v_lshl_add_u64 v[54:55], v[54:55], 0, s[82:83]
	v_lshl_add_u64 v[64:65], v[64:65], 0, s[82:83]
	s_mov_b64 s[8:9], 0x1000
	v_lshl_add_u64 v[130:131], v[54:55], 0, v[8:9]
	v_add_u32_e32 v54, s18, v110
	v_lshl_add_u64 v[64:65], v[64:65], 0, s[8:9]
	s_add_i32 s8, s29, s24
	s_mov_b32 s9, s83
	v_mad_i64_i32 v[54:55], s[14:15], v54, s13, v[62:63]
	v_readlane_b32 s52, v252, 36
	s_lshl_b32 s20, s28, 7
	s_lshl_b64 s[8:9], s[8:9], 9
	s_lshl_b32 s14, s28, 9
	v_readlane_b32 s58, v252, 42
	v_readlane_b32 s59, v252, 43
	s_add_u32 s28, s58, s14
	v_readlane_b32 s56, v252, 40
	s_addc_u32 s29, s59, 0
	v_lshl_add_u64 v[54:55], v[54:55], 0, s[82:83]
	v_readlane_b32 s57, v252, 41
	s_add_u32 s14, s56, s14
	v_lshl_add_u64 v[134:135], v[54:55], 0, v[8:9]
	s_addc_u32 s15, s57, 0
	v_lshlrev_b32_e32 v54, 2, v67
	v_mov_b32_e32 v55, v9
	v_lshl_add_u64 v[138:139], s[14:15], 0, v[54:55]
	s_add_u32 s14, s30, s82
	s_addc_u32 s15, s31, 0
	v_and_b32_e32 v61, 0xf0, v61
	v_lshl_or_b32 v68, v53, 6, v52
	v_lshl_or_b32 v53, v53, 7, v52
	v_and_b32_e32 v116, -8, v57
	v_and_b32_e32 v118, -8, v56
	v_lshl_add_u64 v[140:141], s[14:15], 0, v[8:9]
	s_sub_i32 s14, s26, s27
	v_add_u32_e32 v61, 16, v61
	v_lshl_add_u32 v66, v114, 1, 16
	v_sub_u32_e32 v70, v69, v112
	v_mul_lo_u32 v50, v50, s19
	v_ashrrev_i32_e32 v105, 31, v104
	v_ashrrev_i32_e32 v117, 31, v116
	v_ashrrev_i32_e32 v119, 31, v118
	v_ashrrev_i32_e32 v121, 31, v120
	v_mul_lo_u32 v56, v68, s21
	v_mul_lo_u32 v53, v53, s19
	v_add_u32_e32 v8, v51, v52
	s_sub_i32 s18, s14, 63
	s_add_i32 s14, s34, 64
	v_mov_b32_e32 v158, 0
	v_cmp_gt_u32_e64 s[40:41], 16, v114
	v_cmp_gt_i32_e64 s[42:43], 16, v102
	v_lshl_add_u64 v[124:125], v[104:105], 1, v[64:65]
	v_cmp_gt_i32_e64 s[44:45], 16, v106
	v_lshl_add_u64 v[128:129], v[116:117], 1, v[64:65]
	v_cmp_gt_i32_e64 s[46:47], 16, v108
	v_lshl_add_u64 v[132:133], v[118:119], 1, v[64:65]
	v_cmp_gt_i32_e64 s[48:49], 16, v110
	v_lshl_add_u64 v[136:137], v[120:121], 1, v[64:65]
	v_ashrrev_i32_e32 v107, 31, v106
	v_ashrrev_i32_e32 v109, 31, v108
	v_ashrrev_i32_e32 v111, 31, v110
	v_sub_u32_e32 v159, v8, v101
	v_add_u32_e32 v160, s14, v110
	v_add_u32_e32 v161, s14, v108
	v_add_u32_e32 v162, s14, v106
	v_add_u32_e32 v163, s14, v102
	v_add_u32_e32 v164, s14, v114
	v_mov_b32_e32 v8, 0xff800000
	s_mov_b32 s19, 0
	v_add_u32_e32 v165, v61, v71
	v_add_u32_e32 v166, v66, v60
	v_add_u32_e32 v167, v61, v72
	v_add_u32_e32 v168, v66, v59
	v_add_u32_e32 v169, v61, v73
	v_add_u32_e32 v170, v66, v50
	v_add_u32_e32 v171, v61, v74
	v_add_u32_e32 v172, v66, v58
	v_mul_u32_u24_e32 v166, 0x90, v104
	v_add_u32_e32 v166, v66, v166
	v_add_u32_e32 v168, 0x480, v166
	v_add_u32_e32 v170, 0x900, v166
	v_add_u32_e32 v172, 0xd80, v166
	s_lshl_b32 s82, s20, 1
	v_add_u32_e32 v173, v69, v56
	v_add_u32_e32 v174, v70, v53
	s_mov_b32 s21, 0
	v_mov_b32_e32 v78, 0
	v_mov_b32_e32 v79, v158
	v_mov_b32_e32 v80, v158
	v_mov_b32_e32 v81, v158
	v_mov_b32_e32 v74, 0
	v_mov_b32_e32 v75, v158
	v_mov_b32_e32 v76, v158
	v_mov_b32_e32 v77, v158
	v_mov_b32_e32 v70, 0
	v_mov_b32_e32 v71, v158
	v_mov_b32_e32 v72, v158
	v_mov_b32_e32 v73, v158
	v_mov_b32_e32 v66, 0
	v_mov_b32_e32 v67, v158
	v_mov_b32_e32 v68, v158
	v_mov_b32_e32 v69, v158
	v_mov_b32_e32 v58, 0
	v_mov_b32_e32 v59, v158
	v_mov_b32_e32 v60, v158
	v_mov_b32_e32 v61, v158
	v_mov_b32_e32 v54, 0
	v_mov_b32_e32 v55, v158
	v_mov_b32_e32 v56, v158
	v_mov_b32_e32 v57, v158
	v_mov_b32_e32 v50, 0
	v_mov_b32_e32 v51, v158
	v_mov_b32_e32 v52, v158
	v_mov_b32_e32 v53, v158
	v_mov_b32_e32 v62, 0
	v_mov_b32_e32 v63, v158
	v_mov_b32_e32 v64, v158
	v_mov_b32_e32 v65, v158
	s_mov_b32 s26, 0xff800000
	v_readlane_b32 s53, v252, 37
	v_readlane_b32 s54, v252, 38
	v_readlane_b32 s55, v252, 39
	v_readlane_b32 s60, v252, 44
	v_readlane_b32 s61, v252, 45
	v_readlane_b32 s62, v252, 46
	v_readlane_b32 s63, v252, 47
	v_readlane_b32 s64, v252, 48
	v_readlane_b32 s65, v252, 49
	v_readlane_b32 s66, v252, 50
	v_readlane_b32 s67, v252, 51
